# MIX loop: thread 0's next-unit atomic and chain head/ready polls share one round trip
# speedup vs baseline: 1.0334x; 1.0009x over previous
; __device__ __forceinline__ unsigned lane_lo_() { unsigned l; asm volatile("v_mbcnt_lo_u32_b32 %0, -1, 0" : "=v"(l)); return l; }
; __global__ void __launch_bounds__(512, 2) mega_fwd(Args args) {
;     ...
;               unsigned l0_ = lane_lo_(); asm volatile("" : "+v"(l0_));
;               const bool t0 = F.wave == 0 && l0_ == 0u;
;               unsigned nx = 0u, hd = 0u, rd = 0u;
;               if (t0) { if (kq < 5) nx = __hip_atomic_fetch_add(q + 64 * qk, 1u, RLX_AGENT); if (chain_open) { hd = __hip_atomic_load(ch, RLX_AGENT); rd = __hip_atomic_load(ch + 64, RLX_AGENT); } }
.LBB0_1008:
	s_add_i32 s3, s4, -3
	s_cmp_lt_u32 s3, 2
	s_cselect_b64 s[8:9], -1, 0
	s_and_b64 s[8:9], s[74:75], s[8:9]
	s_sub_i32 s3, 7, s4
	s_and_b64 s[8:9], s[8:9], exec
	v_mbcnt_lo_u32_b32 v1, -1, 0
	v_readlane_b32 s8, v253, 30
	v_readlane_b32 s9, v253, 31
	v_cmp_eq_u32_e32 vcc, 0, v1
	s_cselect_b32 s3, s3, s4
	v_mov_b32_e32 v214, 0
	s_and_b64 s[62:63], s[8:9], vcc
	s_mov_b64 s[14:15], -1
	v_mov_b32_e32 v183, 0
	s_and_saveexec_b64 s[8:9], s[62:63]
	s_cbranch_execz .LBB0_1017
	v_mov_b32_e32 v214, 0
	s_mov_b32 s100, 0
	s_andn2_b64 vcc, exec, s[10:11]
	s_cbranch_vccnz .LBB0_1013
	s_mov_b64 s[12:13], exec
	v_mbcnt_lo_u32_b32 v1, s12, 0
	v_mbcnt_hi_u32_b32 v1, s13, v1
	v_cmp_eq_u32_e32 vcc, 0, v1
	s_and_saveexec_b64 s[10:11], vcc
	s_cbranch_execz .LBB0_1012
	s_lshl_b32 s14, s3, 6
	s_ashr_i32 s15, s14, 31
	s_lshl_b64 s[14:15], s[14:15], 2
	v_readlane_b32 s16, v252, 2
	v_readlane_b32 s17, v252, 3
	s_add_u32 s14, s16, s14
	s_addc_u32 s15, s17, s15
	s_bcnt1_i32_b64 s12, s[12:13]
	v_mov_b32_e32 v2, s12
	global_atomic_add v2, v0, v2, s[14:15] sc0
.LBB0_1012:
	s_or_b64 exec, exec, s[10:11]
	s_mov_b32 s100, 1

; __global__ void __launch_bounds__(512, 2) mega_fwd(Args args) {
;     ...
;               if (t0) { if (kq < 5) nx = __hip_atomic_fetch_add(q + 64 * qk, 1u, RLX_AGENT); if (chain_open) { hd = __hip_atomic_load(ch, RLX_AGENT); rd = __hip_atomic_load(ch + 64, RLX_AGENT); } }
.LBB0_1016:
	s_cmp_eq_u32 s100, 0
	s_cbranch_scc1 .Lgrab_wait_done
	s_waitcnt vmcnt(0)
	v_readfirstlane_b32 s100, v2
	s_nop 1
	v_mov_b32_e32 v214, s100
